# gate/up GEMM phases: first two counted waits of every tile after the first allow the previous tile's 8 in-flight epilogue stores (vmcnt 16) instead of stalling on their acknowledgement
# baseline (speedup 1.0000x reference)
; #define PG8_STAGE(bufoff, gbase, voff) do { _Pragma("unroll") for (int _i = 0; _i < 2; ++_i) \
;         __builtin_amdgcn_global_load_lds((const unsigned*)((const char*)(gbase) + (voff)[_i]), (LAS unsigned*)(lds + (bufoff) + ldsw + _i * 8192), 16, 0, 0); } while (0)
; #define PG8_WAIT_V(n) asm volatile("s_waitcnt vmcnt(" #n ")" ::: "memory")
; #define PG8_BAR __builtin_amdgcn_s_barrier()
; template <class Epi, bool ALIGN_EPI>
; __device__ __forceinline__ void gemm_phase(LAS unsigned char* lds, const Gemm g, const StaticOrder& S, const Epi& E) {
;     ...
;     for (int i = 0; i < 2; ++i) { int R, C; stage_rc(tid * 16 + i * 8192, R, C); const int Rb = Epi::PERM ? ((R & ~31) + perm32(R & 31)) : R;
;         voffA[i] = (unsigned)(R * K + C) * 2u; voffB[i] = (unsigned)(Rb * K + C) * 2u; }
;     const size_t kstep = (size_t)(BK * 2);
;     const size_t hstep = (size_t)HALF * K * 2;
;     const size_t tstep = 2 * hstep;
;     const unsigned ldsw = (unsigned)wid * 1024u;
;     const int aoff = lds_byte(wr * 64 + fr, fq * 8), boff = lds_byte(wc * 32 + fr, fq * 8);
;     ...
;     const char* cA = (const char*)g.A + (size_t)cur.pm * tstep; const char* cB = (const char*)g.Bt + (size_t)cur.pn * tstep;
;     PG8_STAGE(PG8_SB(0, 0), cB, voffB); PG8_STAGE(PG8_SB(0, 1), cB + hstep, voffB); PG8_STAGE(PG8_SA(0, 0), cA, voffA); PG8_STAGE(PG8_SA(0, 1), cA + hstep, voffA);
;     if (wr == 1) PG8_BAR;
;     PG8_WAIT_V(2); PG8_BAR;
;     PG8_STAGE(PG8_SB(1, 0), cB + kstep, voffB); PG8_STAGE(PG8_SA(1, 0), cA + kstep, voffA); PG8_STAGE(PG8_SB(1, 1), cB + hstep + kstep, voffB);
;     PG8_WAIT_V(6); PG8_BAR;
;     for (;;) {
.LBB0_603:
	s_lshl_b32 s5, s11, 5
	s_mov_b64 s[56:57], 0x80
	s_and_b32 s11, s5, 0x60
	s_add_i32 m0, s70, 0x18000
	v_lshl_add_u64 v[8:9], v[8:9], 0, s[56:57]
	s_ashr_i32 s77, s3, 31
	s_lshl_b32 s14, s10, 13
	s_lshl_b32 s15, s11, 7
	s_waitcnt vmcnt(2)
	s_barrier
	global_load_lds_dwordx4 v[8:9], off
	v_lshl_add_u64 v[6:7], v[6:7], 0, s[56:57]
	s_add_i32 m0, s70, 0x1a000
	s_add_i32 s78, s70, 0x8000
	s_add_i32 s79, s70, 0xa000
	global_load_lds_dwordx4 v[6:7], off
	v_lshl_add_u64 v[2:3], v[2:3], 0, s[56:57]
	s_mov_b32 m0, s78
	s_add_u32 s12, s8, 0x40080
	global_load_lds_dwordx4 v[2:3], off
	v_lshl_add_u64 v[2:3], v[4:5], 0, s[56:57]
	s_mov_b32 m0, s79
	s_addc_u32 s13, s9, 0
	global_load_lds_dwordx4 v[2:3], off
	s_add_i32 m0, s70, 0x1c000
	v_lshl_add_u64 v[2:3], s[12:13], 0, v[132:133]
	global_load_lds_dwordx4 v[2:3], off
	v_lshl_add_u64 v[2:3], s[12:13], 0, v[136:137]
	s_add_i32 m0, s70, 0x1e000
	s_sext_i32_i16 s5, s0
	global_load_lds_dwordx4 v[2:3], off
	v_and_b32_e32 v2, 15, v162
	v_lshlrev_b32_e32 v3, 1, v13
	v_lshlrev_b32_e32 v4, 6, v162
	s_movk_i32 s0, 0x3c0
	v_and_or_b32 v4, v4, s0, v3
	v_and_b32_e32 v5, 32, v163
	v_lshl_or_b32 v165, s10, 6, v2
	v_lshl_or_b32 v2, v2, 6, v3
	v_lshlrev_b32_e32 v3, 8, v162
	v_bitop3_b32 v166, s15, v4, v5 bitop3:0xf6
	v_and_b32_e32 v3, 0x38000, v3
	v_lshlrev_b32_e32 v4, 11, v12
	v_or3_b32 v3, v10, v3, v4
	v_add_u32_e32 v138, v3, v11
	v_lshlrev_b32_e32 v3, 4, v14
	s_waitcnt vmcnt(6)
	s_cmpk_lt_u32 s1, 0x100
	v_and_b32_e32 v3, 0x78000, v3
	v_bitop3_b32 v2, v2, s14, v5 bitop3:0xde
	s_cselect_b64 s[58:59], -1, 0
	v_or3_b32 v3, v10, v3, v4
	s_add_i32 s80, 0, 0x10000
	s_add_i32 s81, 0, 0x14000
	v_or_b32_e32 v167, s11, v13
	v_mov_b32_e32 v139, v133
	v_add_u32_e32 v140, v3, v11
	v_mov_b32_e32 v141, v133
	v_mov_b64_e32 v[142:143], 0xb00
	v_mov_b64_e32 v[144:145], 0xaff
	v_add_u32_e32 v168, s80, v166
	v_add_u32_e32 v169, s81, v166
	v_add_u32_e32 v170, 0, v2
	v_mov_b32_e32 v171, 0x358637bd
	s_mov_b32 s82, 0x800000
	s_movk_i32 s83, 0x1600
	s_barrier
	s_mov_b32 s98, 0
	s_branch .LBB0_606

; #define PG8_BAR __builtin_amdgcn_s_barrier()
; template <class Epi, bool ALIGN_EPI>
; __device__ __forceinline__ void gemm_phase(LAS unsigned char* lds, const Gemm g, const StaticOrder& S, const Epi& E) {
;     ...
;         if (!has_next) break;
; #pragma unroll
;         for (int a = 0; a < 2; ++a)
; #pragma unroll
;             for (int b = 0; b < 2; ++b)
; #pragma unroll
;                 for (int m = 0; m < 4; ++m)
; #pragma unroll
;                     for (int n = 0; n < 2; ++n) acc[a][b][m][n] = (f32x4){0.f, 0.f, 0.f, 0.f};
;         cur = nxt; cA = nA; cB = nB; ++ui;
;         if constexpr (ALIGN_EPI) { if (wr == 1) PG8_BAR; }
;     }
.LBB0_605:
	s_mov_b32 s98, 1
	s_andn2_b64 vcc, exec, s[0:1]
	s_mov_b32 s5, s60
	s_mov_b32 s4, s62
	s_mov_b64 s[8:9], s[66:67]
	s_mov_b64 s[6:7], s[64:65]
	s_cbranch_vccz .LBB0_615

; #define PG8_STAGE(bufoff, gbase, voff) do { _Pragma("unroll") for (int _i = 0; _i < 2; ++_i) \
;         __builtin_amdgcn_global_load_lds((const unsigned*)((const char*)(gbase) + (voff)[_i]), (LAS unsigned*)(lds + (bufoff) + ldsw + _i * 8192), 16, 0, 0); } while (0)
; #define PG8_LDA(dst, b, h) do { _Pragma("unroll") for (int m = 0; m < 4; ++m) _Pragma("unroll") for (int k = 0; k < 2; ++k) dst[m][k] = *(const LAS bf16x8*)(lds + PG8_SA(b, h) + aoff + m * 2048 + k * 1024); } while (0)
; #define PG8_LDB(dst, b, h) do { _Pragma("unroll") for (int n = 0; n < 2; ++n) _Pragma("unroll") for (int k = 0; k < 2; ++k) dst[n][k] = *(const LAS bf16x8*)(lds + PG8_SB(b, h) + boff + n * 2048 + k * 1024); } while (0)
; #define PG8_MMA(ai, bj, At, Bt) do { __builtin_amdgcn_s_setprio(3); _Pragma("unroll") for (int m = 0; m < 4; ++m) _Pragma("unroll") for (int n = 0; n < 2; ++n) _Pragma("unroll") for (int k = 0; k < 2; ++k) \
;         acc[ai][bj][m][n] = __builtin_amdgcn_mfma_f32_16x16x32_bf16(Bt[n][k], At[m][k], acc[ai][bj][m][n], 0, 0, 0); __builtin_amdgcn_s_setprio(0); } while (0)
; #define PG8_WAIT_V(n) asm volatile("s_waitcnt vmcnt(" #n ")" ::: "memory")
; #define PG8_WAIT_L(n) asm volatile("s_waitcnt lgkmcnt(" #n ")" ::: "memory")
; template <class Epi, bool ALIGN_EPI>
; __device__ __forceinline__ void gemm_phase(LAS unsigned char* lds, const Gemm g, const StaticOrder& S, const Epi& E) {
;     ...
;         const bool has_next = S.next(ui + 1, nxt);
;         const char* nA = has_next ? (const char*)g.A + (size_t)nxt.pm * tstep : cA; const char* nB = has_next ? (const char*)g.Bt + (size_t)nxt.pn * tstep : cB;
;         for (int t = 0; t < nt; t += 2) {
;             const bool last = (t == nt - 2);
;             const char* a1 = cA + (size_t)(t + 1) * kstep;
;             const char* a2 = last ? nA : cA + (size_t)(t + 2) * kstep; const char* b2 = last ? nB : cB + (size_t)(t + 2) * kstep;
;             const char* a3 = a2 + kstep; const char* b3 = b2 + kstep;
;             PG8_LDB(B0, 0, 0); PG8_LDB(B1, 0, 1); PG8_SCHED; PG8_LDA(At, 0, 0); PG8_STAGE(PG8_SA(1, 1), a1 + hstep, voffA);
;             PG8_WAIT_V(8); PG8_WAIT_L(0); PG8_BAR; PG8_MMA(0, 0, At, B0); PG8_MMA(0, 1, At, B1); PG8_BAR; PG8_SCHED;
;             PG8_LDA(At, 0, 1); PG8_STAGE(PG8_SB(0, 0), b2, voffB); PG8_STAGE(PG8_SB(0, 1), b2 + hstep, voffB); PG8_STAGE(PG8_SA(0, 0), a2, voffA);
.LBB0_608:
	s_ashr_i32 s63, s62, 31
	s_lshl_b64 s[10:11], s[62:63], 19
	s_add_u32 s64, s34, s10
	s_addc_u32 s65, s35, s11
	s_and_b64 s[10:11], s[0:1], exec
	s_cselect_b32 s12, s65, s7
	s_cselect_b32 s13, s64, s6
	s_ashr_i32 s61, s60, 31
	s_lshl_b64 s[10:11], s[60:61], 19
	s_add_u32 s66, s52, s10
	s_addc_u32 s67, s53, s11
	s_and_b64 s[10:11], s[0:1], exec
	s_cselect_b32 s14, s67, s9
	s_cselect_b32 s15, s66, s8
	s_add_u32 s6, s6, 0x40080
	s_addc_u32 s7, s7, 0
	s_add_u32 s16, s8, 0x100
	s_addc_u32 s17, s9, 0
	s_mov_b32 s61, -2
	ds_read_b128 v[146:149], v168
	ds_read_b128 v[150:153], v168 offset:1024
	ds_read_b128 v[154:157], v168 offset:2048
	ds_read_b128 v[158:161], v168 offset:3072
	ds_read_b128 v[172:175], v169
	ds_read_b128 v[176:179], v169 offset:1024
	ds_read_b128 v[180:183], v169 offset:2048
	ds_read_b128 v[184:187], v169 offset:3072
	s_add_u32 s8, s6, 0xfffc0080
	s_addc_u32 s9, s7, -1
	s_cmp_eq_u32 s61, 12
	s_cselect_b32 s11, s12, s9
	s_cselect_b32 s10, s13, s8
	s_cselect_b32 s9, s14, s17
	s_cselect_b32 s8, s15, s16
	v_lshl_add_u64 v[220:221], s[6:7], 0, v[138:139]
	s_add_i32 m0, s70, 0xc000
	ds_read_b128 v[188:191], v170
	ds_read_b128 v[192:195], v170 offset:1024
	ds_read_b128 v[196:199], v170 offset:2048
	ds_read_b128 v[200:203], v170 offset:3072
	ds_read_b128 v[204:207], v170 offset:4096
	ds_read_b128 v[208:211], v170 offset:5120
	ds_read_b128 v[212:215], v170 offset:6144
	ds_read_b128 v[216:219], v170 offset:7168
	global_load_lds_dwordx4 v[220:221], off
	v_lshl_add_u64 v[220:221], s[6:7], 0, v[140:141]
	s_add_i32 m0, s70, 0xe000
	s_nop 0
	global_load_lds_dwordx4 v[220:221], off
	s_cmp_lg_u32 s98, 0
	s_cbranch_scc1 .Lmy_rw_p4_0a
	s_waitcnt vmcnt(8)
	s_branch .Lmy_rw_p4_0b
.Lmy_rw_p4_0a:
	s_waitcnt vmcnt(16)
.Lmy_rw_p4_0b:
	s_waitcnt lgkmcnt(0)
	s_barrier
	s_setprio 3
	s_waitcnt lgkmcnt(0)
	v_mfma_f32_16x16x32_bf16 v[126:129], v[146:149], v[188:191], 0
	v_mfma_f32_16x16x32_bf16 v[118:121], v[154:157], v[188:191], 0
	v_mfma_f32_16x16x32_bf16 v[110:113], v[146:149], v[196:199], 0
	v_mfma_f32_16x16x32_bf16 v[102:105], v[154:157], v[196:199], 0
	v_mfma_f32_16x16x32_bf16 v[94:97], v[146:149], v[204:207], 0
	v_mfma_f32_16x16x32_bf16 v[86:89], v[154:157], v[204:207], 0
	v_mfma_f32_16x16x32_bf16 v[78:81], v[146:149], v[212:215], 0
	v_mfma_f32_16x16x32_bf16 v[70:73], v[154:157], v[212:215], 0
	v_mfma_f32_16x16x32_bf16 v[126:129], v[150:153], v[192:195], v[126:129]
	v_mfma_f32_16x16x32_bf16 v[118:121], v[158:161], v[192:195], v[118:121]
	v_mfma_f32_16x16x32_bf16 v[110:113], v[150:153], v[200:203], v[110:113]
	v_mfma_f32_16x16x32_bf16 v[102:105], v[158:161], v[200:203], v[102:105]
	v_mfma_f32_16x16x32_bf16 v[94:97], v[150:153], v[208:211], v[94:97]
	v_mfma_f32_16x16x32_bf16 v[86:89], v[158:161], v[208:211], v[86:89]
	v_mfma_f32_16x16x32_bf16 v[78:81], v[150:153], v[216:219], v[78:81]
	v_mfma_f32_16x16x32_bf16 v[70:73], v[158:161], v[216:219], v[70:73]
	v_mfma_f32_16x16x32_bf16 v[122:125], v[172:175], v[188:191], 0
	v_mfma_f32_16x16x32_bf16 v[114:117], v[180:183], v[188:191], 0
	v_mfma_f32_16x16x32_bf16 v[106:109], v[172:175], v[196:199], 0
	v_mfma_f32_16x16x32_bf16 v[98:101], v[180:183], v[196:199], 0
	v_mfma_f32_16x16x32_bf16 v[90:93], v[172:175], v[204:207], 0
	v_mfma_f32_16x16x32_bf16 v[82:85], v[180:183], v[204:207], 0
	v_mfma_f32_16x16x32_bf16 v[74:77], v[172:175], v[212:215], 0
	v_mfma_f32_16x16x32_bf16 v[66:69], v[180:183], v[212:215], 0
	v_mfma_f32_16x16x32_bf16 v[122:125], v[176:179], v[192:195], v[122:125]
	v_mfma_f32_16x16x32_bf16 v[114:117], v[184:187], v[192:195], v[114:117]
	v_mfma_f32_16x16x32_bf16 v[106:109], v[176:179], v[200:203], v[106:109]
	v_mfma_f32_16x16x32_bf16 v[98:101], v[184:187], v[200:203], v[98:101]
	v_mfma_f32_16x16x32_bf16 v[90:93], v[176:179], v[208:211], v[90:93]
	v_mfma_f32_16x16x32_bf16 v[82:85], v[184:187], v[208:211], v[82:85]
	v_mfma_f32_16x16x32_bf16 v[74:77], v[176:179], v[216:219], v[74:77]
	v_mfma_f32_16x16x32_bf16 v[66:69], v[184:187], v[216:219], v[66:69]
	s_setprio 0
	s_barrier
	s_add_i32 s63, s80, s33
	v_lshl_add_u64 v[220:221], s[8:9], 0, v[132:133]
	s_mov_b32 m0, s63
	ds_read_b128 v[188:191], v170 offset:16384
	ds_read_b128 v[192:195], v170 offset:17408
	ds_read_b128 v[196:199], v170 offset:18432
	ds_read_b128 v[200:203], v170 offset:19456
	ds_read_b128 v[204:207], v170 offset:20480
	ds_read_b128 v[208:211], v170 offset:21504
	ds_read_b128 v[212:215], v170 offset:22528
	ds_read_b128 v[216:219], v170 offset:23552
	global_load_lds_dwordx4 v[220:221], off
	s_add_i32 m0, s63, 0x2000
	s_add_u32 s84, s8, 0x40000
	v_lshl_add_u64 v[222:223], s[8:9], 0, v[136:137]
	s_addc_u32 s85, s9, 0
	s_add_i32 s63, s81, s33
	global_load_lds_dwordx4 v[222:223], off
	v_lshl_add_u64 v[224:225], s[84:85], 0, v[132:133]
	s_mov_b32 m0, s63
	v_lshl_add_u64 v[226:227], s[10:11], 0, v[134:135]
	global_load_lds_dwordx4 v[224:225], off
	v_lshl_add_u64 v[224:225], s[84:85], 0, v[136:137]
	s_add_i32 m0, s63, 0x2000
	s_nop 0
	global_load_lds_dwordx4 v[224:225], off
	v_lshl_add_u64 v[224:225], s[10:11], 0, v[130:131]
	s_mov_b32 m0, s70
	s_nop 0
	global_load_lds_dwordx4 v[224:225], off
	s_mov_b32 m0, s71
	s_nop 0
	global_load_lds_dwordx4 v[226:227], off
	s_cmp_lg_u32 s98, 0
	s_cbranch_scc1 .Lmy_rw_p4_1a
	s_waitcnt vmcnt(8)
	s_branch .Lmy_rw_p4_1b

; #define PG8_STAGE(bufoff, gbase, voff) do { _Pragma("unroll") for (int _i = 0; _i < 2; ++_i) \
;         __builtin_amdgcn_global_load_lds((const unsigned*)((const char*)(gbase) + (voff)[_i]), (LAS unsigned*)(lds + (bufoff) + ldsw + _i * 8192), 16, 0, 0); } while (0)
; #define PG8_LDA(dst, b, h) do { _Pragma("unroll") for (int m = 0; m < 4; ++m) _Pragma("unroll") for (int k = 0; k < 2; ++k) dst[m][k] = *(const LAS bf16x8*)(lds + PG8_SA(b, h) + aoff + m * 2048 + k * 1024); } while (0)
; #define PG8_LDB(dst, b, h) do { _Pragma("unroll") for (int n = 0; n < 2; ++n) _Pragma("unroll") for (int k = 0; k < 2; ++k) dst[n][k] = *(const LAS bf16x8*)(lds + PG8_SB(b, h) + boff + n * 2048 + k * 1024); } while (0)
; #define PG8_MMA(ai, bj, At, Bt) do { __builtin_amdgcn_s_setprio(3); _Pragma("unroll") for (int m = 0; m < 4; ++m) _Pragma("unroll") for (int n = 0; n < 2; ++n) _Pragma("unroll") for (int k = 0; k < 2; ++k) \
;         acc[ai][bj][m][n] = __builtin_amdgcn_mfma_f32_16x16x32_bf16(Bt[n][k], At[m][k], acc[ai][bj][m][n], 0, 0, 0); __builtin_amdgcn_s_setprio(0); } while (0)
; #define PG8_WAIT_V(n) asm volatile("s_waitcnt vmcnt(" #n ")" ::: "memory")
; #define PG8_WAIT_L(n) asm volatile("s_waitcnt lgkmcnt(" #n ")" ::: "memory")
; #define PG8_BAR __builtin_amdgcn_s_barrier()
; #define PG8_SCHED __builtin_amdgcn_sched_barrier(0)
; template <class Epi, bool ALIGN_EPI>
; __device__ __forceinline__ void gemm_phase(LAS unsigned char* lds, const Gemm g, const StaticOrder& S, const Epi& E) {
;     ...
;             PG8_LDA(At, 0, 1); PG8_STAGE(PG8_SB(0, 0), b2, voffB); PG8_STAGE(PG8_SB(0, 1), b2 + hstep, voffB); PG8_STAGE(PG8_SA(0, 0), a2, voffA);
;             PG8_WAIT_V(8); PG8_WAIT_L(0); PG8_BAR; PG8_MMA(1, 0, At, B0); PG8_MMA(1, 1, At, B1); PG8_BAR; PG8_SCHED;
;             PG8_LDB(B0, 1, 0); PG8_LDB(B1, 1, 1); PG8_SCHED; PG8_LDA(At, 1, 0); PG8_STAGE(PG8_SA(0, 1), a2 + hstep, voffA);
;             PG8_WAIT_V(8); PG8_WAIT_L(0); PG8_BAR; PG8_MMA(0, 0, At, B0); PG8_MMA(0, 1, At, B1); PG8_BAR; PG8_SCHED;
.Lmy_rw_p4_1b:
	s_waitcnt lgkmcnt(0)
	s_barrier
	s_setprio 3
	s_waitcnt lgkmcnt(0)
	v_mfma_f32_16x16x32_bf16 v[62:65], v[146:149], v[188:191], 0
	v_mfma_f32_16x16x32_bf16 v[54:57], v[154:157], v[188:191], 0
	v_mfma_f32_16x16x32_bf16 v[46:49], v[146:149], v[196:199], 0
	v_mfma_f32_16x16x32_bf16 v[38:41], v[154:157], v[196:199], 0
	v_mfma_f32_16x16x32_bf16 v[30:33], v[146:149], v[204:207], 0
	v_mfma_f32_16x16x32_bf16 v[22:25], v[154:157], v[204:207], 0
	v_mfma_f32_16x16x32_bf16 v[14:17], v[146:149], v[212:215], 0
	v_mfma_f32_16x16x32_bf16 v[6:9], v[154:157], v[212:215], 0
	v_mfma_f32_16x16x32_bf16 v[62:65], v[150:153], v[192:195], v[62:65]
	v_mfma_f32_16x16x32_bf16 v[54:57], v[158:161], v[192:195], v[54:57]
	v_mfma_f32_16x16x32_bf16 v[46:49], v[150:153], v[200:203], v[46:49]
	v_mfma_f32_16x16x32_bf16 v[38:41], v[158:161], v[200:203], v[38:41]
	v_mfma_f32_16x16x32_bf16 v[30:33], v[150:153], v[208:211], v[30:33]
	v_mfma_f32_16x16x32_bf16 v[22:25], v[158:161], v[208:211], v[22:25]
	v_mfma_f32_16x16x32_bf16 v[14:17], v[150:153], v[216:219], v[14:17]
	v_mfma_f32_16x16x32_bf16 v[6:9], v[158:161], v[216:219], v[6:9]
	v_mfma_f32_16x16x32_bf16 v[58:61], v[172:175], v[188:191], 0
	v_mfma_f32_16x16x32_bf16 v[50:53], v[180:183], v[188:191], 0
	v_mfma_f32_16x16x32_bf16 v[42:45], v[172:175], v[196:199], 0
	v_mfma_f32_16x16x32_bf16 v[34:37], v[180:183], v[196:199], 0
	v_mfma_f32_16x16x32_bf16 v[26:29], v[172:175], v[204:207], 0
	v_mfma_f32_16x16x32_bf16 v[18:21], v[180:183], v[204:207], 0
	v_mfma_f32_16x16x32_bf16 v[10:13], v[172:175], v[212:215], 0
	v_mfma_f32_16x16x32_bf16 v[2:5], v[180:183], v[212:215], 0
	v_mfma_f32_16x16x32_bf16 v[58:61], v[176:179], v[192:195], v[58:61]
	v_mfma_f32_16x16x32_bf16 v[50:53], v[184:187], v[192:195], v[50:53]
	v_mfma_f32_16x16x32_bf16 v[42:45], v[176:179], v[200:203], v[42:45]
	v_mfma_f32_16x16x32_bf16 v[34:37], v[184:187], v[200:203], v[34:37]
	v_mfma_f32_16x16x32_bf16 v[26:29], v[176:179], v[208:211], v[26:29]
	v_mfma_f32_16x16x32_bf16 v[18:21], v[184:187], v[208:211], v[18:21]
	v_mfma_f32_16x16x32_bf16 v[10:13], v[176:179], v[216:219], v[10:13]
	v_mfma_f32_16x16x32_bf16 v[2:5], v[184:187], v[216:219], v[2:5]
	s_setprio 0
	s_barrier
	s_add_i32 s63, 0, 0x18000
	s_add_i32 s84, 0, 0x1c000
	v_add_u32_e32 v158, s63, v166
	v_add_u32_e32 v184, s84, v166
	ds_read_b128 v[146:149], v158
	ds_read_b128 v[150:153], v158 offset:1024
	ds_read_b128 v[154:157], v158 offset:2048
	ds_read_b128 v[158:161], v158 offset:3072
	ds_read_b128 v[172:175], v184
	ds_read_b128 v[176:179], v184 offset:1024
	ds_read_b128 v[180:183], v184 offset:2048
	ds_read_b128 v[184:187], v184 offset:3072
	s_add_u32 s10, s10, 0x40000
	s_addc_u32 s11, s11, 0
	s_mov_b32 m0, s72
	v_lshl_add_u64 v[228:229], s[10:11], 0, v[130:131]
	ds_read_b128 v[188:191], v170 offset:32768
	ds_read_b128 v[192:195], v170 offset:33792
	ds_read_b128 v[196:199], v170 offset:34816
	ds_read_b128 v[200:203], v170 offset:35840
	ds_read_b128 v[204:207], v170 offset:36864
	ds_read_b128 v[208:211], v170 offset:37888
	ds_read_b128 v[212:215], v170 offset:38912
	ds_read_b128 v[216:219], v170 offset:39936
	global_load_lds_dwordx4 v[228:229], off
	v_lshl_add_u64 v[228:229], s[10:11], 0, v[134:135]
	s_mov_b32 m0, s73
	s_nop 0
	global_load_lds_dwordx4 v[228:229], off
	s_waitcnt vmcnt(8)
	s_waitcnt lgkmcnt(0)
	s_barrier
	s_setprio 3
	s_waitcnt lgkmcnt(0)
	v_mfma_f32_16x16x32_bf16 v[126:129], v[146:149], v[188:191], v[126:129]
	v_mfma_f32_16x16x32_bf16 v[118:121], v[154:157], v[188:191], v[118:121]
	v_mfma_f32_16x16x32_bf16 v[110:113], v[146:149], v[196:199], v[110:113]
	v_mfma_f32_16x16x32_bf16 v[102:105], v[154:157], v[196:199], v[102:105]
	v_mfma_f32_16x16x32_bf16 v[94:97], v[146:149], v[204:207], v[94:97]
	v_mfma_f32_16x16x32_bf16 v[86:89], v[154:157], v[204:207], v[86:89]
	v_mfma_f32_16x16x32_bf16 v[78:81], v[146:149], v[212:215], v[78:81]
	v_mfma_f32_16x16x32_bf16 v[70:73], v[154:157], v[212:215], v[70:73]
	v_mfma_f32_16x16x32_bf16 v[126:129], v[150:153], v[192:195], v[126:129]
	v_mfma_f32_16x16x32_bf16 v[118:121], v[158:161], v[192:195], v[118:121]
	v_mfma_f32_16x16x32_bf16 v[110:113], v[150:153], v[200:203], v[110:113]
	v_mfma_f32_16x16x32_bf16 v[102:105], v[158:161], v[200:203], v[102:105]
	v_mfma_f32_16x16x32_bf16 v[94:97], v[150:153], v[208:211], v[94:97]
	v_mfma_f32_16x16x32_bf16 v[86:89], v[158:161], v[208:211], v[86:89]
	v_mfma_f32_16x16x32_bf16 v[78:81], v[150:153], v[216:219], v[78:81]
	v_mfma_f32_16x16x32_bf16 v[70:73], v[158:161], v[216:219], v[70:73]
	v_mfma_f32_16x16x32_bf16 v[122:125], v[172:175], v[188:191], v[122:125]
	v_mfma_f32_16x16x32_bf16 v[114:117], v[180:183], v[188:191], v[114:117]
	v_mfma_f32_16x16x32_bf16 v[106:109], v[172:175], v[196:199], v[106:109]
	v_mfma_f32_16x16x32_bf16 v[98:101], v[180:183], v[196:199], v[98:101]
	v_mfma_f32_16x16x32_bf16 v[90:93], v[172:175], v[204:207], v[90:93]
	v_mfma_f32_16x16x32_bf16 v[82:85], v[180:183], v[204:207], v[82:85]
	v_mfma_f32_16x16x32_bf16 v[74:77], v[172:175], v[212:215], v[74:77]
	v_mfma_f32_16x16x32_bf16 v[66:69], v[180:183], v[212:215], v[66:69]
	v_mfma_f32_16x16x32_bf16 v[122:125], v[176:179], v[192:195], v[122:125]
	v_mfma_f32_16x16x32_bf16 v[114:117], v[184:187], v[192:195], v[114:117]
	v_mfma_f32_16x16x32_bf16 v[106:109], v[176:179], v[200:203], v[106:109]
	v_mfma_f32_16x16x32_bf16 v[98:101], v[184:187], v[200:203], v[98:101]
	v_mfma_f32_16x16x32_bf16 v[90:93], v[176:179], v[208:211], v[90:93]
	v_mfma_f32_16x16x32_bf16 v[82:85], v[184:187], v[208:211], v[82:85]
	v_mfma_f32_16x16x32_bf16 v[74:77], v[176:179], v[216:219], v[74:77]
	v_mfma_f32_16x16x32_bf16 v[66:69], v[184:187], v[216:219], v[66:69]
	s_setprio 0
	s_barrier
; #define PG8_STAGE(bufoff, gbase, voff) do { _Pragma("unroll") for (int _i = 0; _i < 2; ++_i) \
;         __builtin_amdgcn_global_load_lds((const unsigned*)((const char*)(gbase) + (voff)[_i]), (LAS unsigned*)(lds + (bufoff) + ldsw + _i * 8192), 16, 0, 0); } while (0)
; #define PG8_LDA(dst, b, h) do { _Pragma("unroll") for (int m = 0; m < 4; ++m) _Pragma("unroll") for (int k = 0; k < 2; ++k) dst[m][k] = *(const LAS bf16x8*)(lds + PG8_SA(b, h) + aoff + m * 2048 + k * 1024); } while (0)
; #define PG8_MMA(ai, bj, At, Bt) do { __builtin_amdgcn_s_setprio(3); _Pragma("unroll") for (int m = 0; m < 4; ++m) _Pragma("unroll") for (int n = 0; n < 2; ++n) _Pragma("unroll") for (int k = 0; k < 2; ++k) \
;         acc[ai][bj][m][n] = __builtin_amdgcn_mfma_f32_16x16x32_bf16(Bt[n][k], At[m][k], acc[ai][bj][m][n], 0, 0, 0); __builtin_amdgcn_s_setprio(0); } while (0)
; #define PG8_WAIT_V(n) asm volatile("s_waitcnt vmcnt(" #n ")" ::: "memory")
; #define PG8_WAIT_L(n) asm volatile("s_waitcnt lgkmcnt(" #n ")" ::: "memory")
; #define PG8_BAR __builtin_amdgcn_s_barrier()
; #define PG8_SCHED __builtin_amdgcn_sched_barrier(0)
; template <class Epi, bool ALIGN_EPI>
; __device__ __forceinline__ void gemm_phase(LAS unsigned char* lds, const Gemm g, const StaticOrder& S, const Epi& E) {
;     ...
;             PG8_LDA(At, 1, 1); PG8_STAGE(PG8_SB(1, 0), b3, voffB); PG8_STAGE(PG8_SB(1, 1), b3 + hstep, voffB); PG8_STAGE(PG8_SA(1, 0), a3, voffA);
;             PG8_WAIT_V(8); PG8_WAIT_L(0); PG8_BAR; PG8_MMA(1, 0, At, B0); PG8_MMA(1, 1, At, B1); PG8_BAR; PG8_SCHED;
	s_add_i32 s10, s63, s33
	v_lshl_add_u64 v[220:221], v[220:221], 0, s[56:57]
	s_mov_b32 m0, s10
	ds_read_b128 v[188:191], v170 offset:49152
	ds_read_b128 v[192:195], v170 offset:50176
	ds_read_b128 v[196:199], v170 offset:51200
	ds_read_b128 v[200:203], v170 offset:52224
	ds_read_b128 v[204:207], v170 offset:53248
	ds_read_b128 v[208:211], v170 offset:54272
	ds_read_b128 v[212:215], v170 offset:55296
	ds_read_b128 v[216:219], v170 offset:56320
	global_load_lds_dwordx4 v[220:221], off
	s_add_i32 m0, s10, 0x2000
	s_add_u32 s8, s8, 0x40080
	v_lshl_add_u64 v[220:221], v[222:223], 0, s[56:57]
	s_addc_u32 s9, s9, 0
	s_add_i32 s10, s84, s33
	global_load_lds_dwordx4 v[220:221], off
	v_lshl_add_u64 v[220:221], s[8:9], 0, v[132:133]
	s_mov_b32 m0, s10
	s_nop 0
	global_load_lds_dwordx4 v[220:221], off
	v_lshl_add_u64 v[220:221], s[8:9], 0, v[136:137]
	s_add_i32 m0, s10, 0x2000
	s_nop 0
	global_load_lds_dwordx4 v[220:221], off
	v_lshl_add_u64 v[220:221], v[224:225], 0, s[56:57]
	s_mov_b32 m0, s78
	s_nop 0
	global_load_lds_dwordx4 v[220:221], off
	v_lshl_add_u64 v[220:221], v[226:227], 0, s[56:57]
	s_mov_b32 m0, s79
	s_nop 0
	global_load_lds_dwordx4 v[220:221], off
	s_waitcnt vmcnt(8)
	s_waitcnt lgkmcnt(0)
	s_barrier
	s_setprio 3
	s_waitcnt lgkmcnt(0)
	v_mfma_f32_16x16x32_bf16 v[62:65], v[146:149], v[188:191], v[62:65]
	v_mfma_f32_16x16x32_bf16 v[54:57], v[154:157], v[188:191], v[54:57]
	v_mfma_f32_16x16x32_bf16 v[46:49], v[146:149], v[196:199], v[46:49]
	v_mfma_f32_16x16x32_bf16 v[38:41], v[154:157], v[196:199], v[38:41]
	v_mfma_f32_16x16x32_bf16 v[30:33], v[146:149], v[204:207], v[30:33]
	v_mfma_f32_16x16x32_bf16 v[22:25], v[154:157], v[204:207], v[22:25]
	v_mfma_f32_16x16x32_bf16 v[14:17], v[146:149], v[212:215], v[14:17]
	v_mfma_f32_16x16x32_bf16 v[6:9], v[154:157], v[212:215], v[6:9]
	v_mfma_f32_16x16x32_bf16 v[62:65], v[150:153], v[192:195], v[62:65]
	v_mfma_f32_16x16x32_bf16 v[54:57], v[158:161], v[192:195], v[54:57]
	v_mfma_f32_16x16x32_bf16 v[46:49], v[150:153], v[200:203], v[46:49]
	v_mfma_f32_16x16x32_bf16 v[38:41], v[158:161], v[200:203], v[38:41]
	v_mfma_f32_16x16x32_bf16 v[30:33], v[150:153], v[208:211], v[30:33]
	v_mfma_f32_16x16x32_bf16 v[22:25], v[158:161], v[208:211], v[22:25]
	v_mfma_f32_16x16x32_bf16 v[14:17], v[150:153], v[216:219], v[14:17]
	v_mfma_f32_16x16x32_bf16 v[6:9], v[158:161], v[216:219], v[6:9]
	v_mfma_f32_16x16x32_bf16 v[58:61], v[172:175], v[188:191], v[58:61]
	v_mfma_f32_16x16x32_bf16 v[50:53], v[180:183], v[188:191], v[50:53]
	v_mfma_f32_16x16x32_bf16 v[42:45], v[172:175], v[196:199], v[42:45]
	v_mfma_f32_16x16x32_bf16 v[34:37], v[180:183], v[196:199], v[34:37]
	v_mfma_f32_16x16x32_bf16 v[26:29], v[172:175], v[204:207], v[26:29]
	v_mfma_f32_16x16x32_bf16 v[18:21], v[180:183], v[204:207], v[18:21]
	v_mfma_f32_16x16x32_bf16 v[10:13], v[172:175], v[212:215], v[10:13]
	v_mfma_f32_16x16x32_bf16 v[2:5], v[180:183], v[212:215], v[2:5]
	v_mfma_f32_16x16x32_bf16 v[58:61], v[176:179], v[192:195], v[58:61]
	v_mfma_f32_16x16x32_bf16 v[50:53], v[184:187], v[192:195], v[50:53]
	v_mfma_f32_16x16x32_bf16 v[42:45], v[176:179], v[200:203], v[42:45]
	v_mfma_f32_16x16x32_bf16 v[34:37], v[184:187], v[200:203], v[34:37]
	v_mfma_f32_16x16x32_bf16 v[26:29], v[176:179], v[208:211], v[26:29]
	v_mfma_f32_16x16x32_bf16 v[18:21], v[184:187], v[208:211], v[18:21]
	v_mfma_f32_16x16x32_bf16 v[10:13], v[176:179], v[216:219], v[10:13]
	v_mfma_f32_16x16x32_bf16 v[2:5], v[184:187], v[216:219], v[2:5]
	s_setprio 0
	s_barrier
	s_add_i32 s61, s61, 2
	s_add_u32 s6, s6, 0x100
	s_addc_u32 s7, s7, 0
	s_add_u32 s16, s16, 0x100
	s_addc_u32 s17, s17, 0

; #define PG8_STAGE(bufoff, gbase, voff) do { _Pragma("unroll") for (int _i = 0; _i < 2; ++_i) \
;         __builtin_amdgcn_global_load_lds((const unsigned*)((const char*)(gbase) + (voff)[_i]), (LAS unsigned*)(lds + (bufoff) + ldsw + _i * 8192), 16, 0, 0); } while (0)
; #define PG8_WAIT_V(n) asm volatile("s_waitcnt vmcnt(" #n ")" ::: "memory")
; #define PG8_BAR __builtin_amdgcn_s_barrier()
; template <class Epi, bool ALIGN_EPI>
; __device__ __forceinline__ void gemm_phase(LAS unsigned char* lds, const Gemm g, const StaticOrder& S, const Epi& E) {
;     ...
;     for (int i = 0; i < 2; ++i) { int R, C; stage_rc(tid * 16 + i * 8192, R, C); const int Rb = Epi::PERM ? ((R & ~31) + perm32(R & 31)) : R;
;         voffA[i] = (unsigned)(R * K + C) * 2u; voffB[i] = (unsigned)(Rb * K + C) * 2u; }
;     const size_t kstep = (size_t)(BK * 2);
;     const size_t hstep = (size_t)HALF * K * 2;
;     const size_t tstep = 2 * hstep;
;     const unsigned ldsw = (unsigned)wid * 1024u;
;     const int aoff = lds_byte(wr * 64 + fr, fq * 8), boff = lds_byte(wc * 32 + fr, fq * 8);
;     ...
;     const char* cA = (const char*)g.A + (size_t)cur.pm * tstep; const char* cB = (const char*)g.Bt + (size_t)cur.pn * tstep;
;     PG8_STAGE(PG8_SB(0, 0), cB, voffB); PG8_STAGE(PG8_SB(0, 1), cB + hstep, voffB); PG8_STAGE(PG8_SA(0, 0), cA, voffA); PG8_STAGE(PG8_SA(0, 1), cA + hstep, voffA);
;     if (wr == 1) PG8_BAR;
;     PG8_WAIT_V(2); PG8_BAR;
;     PG8_STAGE(PG8_SB(1, 0), cB + kstep, voffB); PG8_STAGE(PG8_SA(1, 0), cA + kstep, voffA); PG8_STAGE(PG8_SB(1, 1), cB + hstep + kstep, voffB);
;     PG8_WAIT_V(6); PG8_BAR;
;     for (;;) {
.LBB0_1422:
	s_lshl_b32 s5, s11, 5
	s_mov_b64 s[36:37], 0x80
	s_and_b32 s11, s5, 0x60
	s_add_i32 m0, s50, 0x18000
	v_lshl_add_u64 v[8:9], v[8:9], 0, s[36:37]
	s_ashr_i32 s55, s3, 31
	s_lshl_b32 s14, s10, 13
	s_lshl_b32 s15, s11, 7
	s_waitcnt vmcnt(2)
	s_barrier
	global_load_lds_dwordx4 v[8:9], off
	v_lshl_add_u64 v[6:7], v[6:7], 0, s[36:37]
	s_add_i32 m0, s50, 0x1a000
	s_add_i32 s56, s50, 0x8000
	s_add_i32 s57, s50, 0xa000
	global_load_lds_dwordx4 v[6:7], off
	v_lshl_add_u64 v[2:3], v[2:3], 0, s[36:37]
	s_mov_b32 m0, s56
	s_add_u32 s12, s8, 0x40080
	global_load_lds_dwordx4 v[2:3], off
	v_lshl_add_u64 v[2:3], v[4:5], 0, s[36:37]
	s_mov_b32 m0, s57
	s_addc_u32 s13, s9, 0
	global_load_lds_dwordx4 v[2:3], off
	s_add_i32 m0, s50, 0x1c000
	v_lshl_add_u64 v[2:3], s[12:13], 0, v[132:133]
	global_load_lds_dwordx4 v[2:3], off
	v_lshl_add_u64 v[2:3], s[12:13], 0, v[136:137]
	s_add_i32 m0, s50, 0x1e000
	s_sext_i32_i16 s5, s0
	global_load_lds_dwordx4 v[2:3], off
	v_and_b32_e32 v2, 15, v162
	v_lshlrev_b32_e32 v3, 1, v13
	v_lshlrev_b32_e32 v4, 6, v162
	s_movk_i32 s0, 0x3c0
	v_and_or_b32 v4, v4, s0, v3
	v_and_b32_e32 v5, 32, v163
	v_lshl_or_b32 v165, s10, 6, v2
	v_lshl_or_b32 v2, v2, 6, v3
	v_lshlrev_b32_e32 v3, 8, v162
	v_bitop3_b32 v166, s15, v4, v5 bitop3:0xf6
	v_and_b32_e32 v3, 0x38000, v3
	v_lshlrev_b32_e32 v4, 11, v12
	v_or3_b32 v3, v10, v3, v4
	v_add_u32_e32 v138, v3, v11
	v_lshlrev_b32_e32 v3, 4, v14
	s_waitcnt vmcnt(6)
	s_cmpk_lt_u32 s1, 0x100
	v_and_b32_e32 v3, 0x78000, v3
	v_bitop3_b32 v2, v2, s14, v5 bitop3:0xde
	s_cselect_b64 s[38:39], -1, 0
	v_or3_b32 v3, v10, v3, v4
	s_add_i32 s58, 0, 0x10000
	s_add_i32 s59, 0, 0x14000
	v_or_b32_e32 v167, s11, v13
	v_mov_b32_e32 v139, v133
	v_add_u32_e32 v140, v3, v11
	v_mov_b32_e32 v141, v133
	v_mov_b64_e32 v[142:143], 0xb00
	v_mov_b64_e32 v[144:145], 0xaff
	v_add_u32_e32 v168, s58, v166
	v_add_u32_e32 v169, s59, v166
	v_add_u32_e32 v170, 0, v2
	v_mov_b32_e32 v171, 0x358637bd
	s_mov_b32 s60, 0x800000
	s_movk_i32 s61, 0x1600
	s_barrier
	s_mov_b32 s98, 0
	s_branch .LBB0_1425

; #define PG8_BAR __builtin_amdgcn_s_barrier()
; template <class Epi, bool ALIGN_EPI>
; __device__ __forceinline__ void gemm_phase(LAS unsigned char* lds, const Gemm g, const StaticOrder& S, const Epi& E) {
;     ...
;         if (!has_next) break;
; #pragma unroll
;         for (int a = 0; a < 2; ++a)
; #pragma unroll
;             for (int b = 0; b < 2; ++b)
; #pragma unroll
;                 for (int m = 0; m < 4; ++m)
; #pragma unroll
;                     for (int n = 0; n < 2; ++n) acc[a][b][m][n] = (f32x4){0.f, 0.f, 0.f, 0.f};
;         cur = nxt; cA = nA; cB = nB; ++ui;
;         if constexpr (ALIGN_EPI) { if (wr == 1) PG8_BAR; }
;     }
.LBB0_1424:
	s_mov_b32 s98, 1
	s_andn2_b64 vcc, exec, s[0:1]
	s_mov_b32 s5, s40
	s_mov_b32 s4, s42
	s_mov_b64 s[8:9], s[46:47]
	s_mov_b64 s[6:7], s[44:45]
	s_cbranch_vccz .LBB0_1434

; #define PG8_STAGE(bufoff, gbase, voff) do { _Pragma("unroll") for (int _i = 0; _i < 2; ++_i) \
;         __builtin_amdgcn_global_load_lds((const unsigned*)((const char*)(gbase) + (voff)[_i]), (LAS unsigned*)(lds + (bufoff) + ldsw + _i * 8192), 16, 0, 0); } while (0)
; #define PG8_LDA(dst, b, h) do { _Pragma("unroll") for (int m = 0; m < 4; ++m) _Pragma("unroll") for (int k = 0; k < 2; ++k) dst[m][k] = *(const LAS bf16x8*)(lds + PG8_SA(b, h) + aoff + m * 2048 + k * 1024); } while (0)
; #define PG8_LDB(dst, b, h) do { _Pragma("unroll") for (int n = 0; n < 2; ++n) _Pragma("unroll") for (int k = 0; k < 2; ++k) dst[n][k] = *(const LAS bf16x8*)(lds + PG8_SB(b, h) + boff + n * 2048 + k * 1024); } while (0)
; #define PG8_MMA(ai, bj, At, Bt) do { __builtin_amdgcn_s_setprio(3); _Pragma("unroll") for (int m = 0; m < 4; ++m) _Pragma("unroll") for (int n = 0; n < 2; ++n) _Pragma("unroll") for (int k = 0; k < 2; ++k) \
;         acc[ai][bj][m][n] = __builtin_amdgcn_mfma_f32_16x16x32_bf16(Bt[n][k], At[m][k], acc[ai][bj][m][n], 0, 0, 0); __builtin_amdgcn_s_setprio(0); } while (0)
; #define PG8_WAIT_V(n) asm volatile("s_waitcnt vmcnt(" #n ")" ::: "memory")
; #define PG8_WAIT_L(n) asm volatile("s_waitcnt lgkmcnt(" #n ")" ::: "memory")
; #define PG8_BAR __builtin_amdgcn_s_barrier()
; #define PG8_SCHED __builtin_amdgcn_sched_barrier(0)
; template <class Epi, bool ALIGN_EPI>
; __device__ __forceinline__ void gemm_phase(LAS unsigned char* lds, const Gemm g, const StaticOrder& S, const Epi& E) {
;     ...
;         const bool has_next = S.next(ui + 1, nxt);
;         const char* nA = has_next ? (const char*)g.A + (size_t)nxt.pm * tstep : cA; const char* nB = has_next ? (const char*)g.Bt + (size_t)nxt.pn * tstep : cB;
;         for (int t = 0; t < nt; t += 2) {
;             const bool last = (t == nt - 2);
;             const char* a1 = cA + (size_t)(t + 1) * kstep;
;             const char* a2 = last ? nA : cA + (size_t)(t + 2) * kstep; const char* b2 = last ? nB : cB + (size_t)(t + 2) * kstep;
;             const char* a3 = a2 + kstep; const char* b3 = b2 + kstep;
;             PG8_LDB(B0, 0, 0); PG8_LDB(B1, 0, 1); PG8_SCHED; PG8_LDA(At, 0, 0); PG8_STAGE(PG8_SA(1, 1), a1 + hstep, voffA);
;             PG8_WAIT_V(8); PG8_WAIT_L(0); PG8_BAR; PG8_MMA(0, 0, At, B0); PG8_MMA(0, 1, At, B1); PG8_BAR; PG8_SCHED;
.LBB0_1427:
	s_ashr_i32 s43, s42, 31
	s_lshl_b64 s[10:11], s[42:43], 19
	s_add_u32 s44, s34, s10
	s_addc_u32 s45, s35, s11
	s_and_b64 s[10:11], s[0:1], exec
	s_cselect_b32 s12, s45, s7
	s_cselect_b32 s13, s44, s6
	s_ashr_i32 s41, s40, 31
	s_lshl_b64 s[10:11], s[40:41], 19
	s_add_u32 s46, s22, s10
	s_addc_u32 s47, s23, s11
	s_and_b64 s[10:11], s[0:1], exec
	s_cselect_b32 s14, s47, s9
	s_cselect_b32 s15, s46, s8
	s_add_u32 s6, s6, 0x40080
	s_addc_u32 s7, s7, 0
	s_add_u32 s16, s8, 0x100
	s_addc_u32 s17, s9, 0
	s_mov_b32 s41, -2
	ds_read_b128 v[146:149], v168
	ds_read_b128 v[150:153], v168 offset:1024
	ds_read_b128 v[154:157], v168 offset:2048
	ds_read_b128 v[158:161], v168 offset:3072
	ds_read_b128 v[172:175], v169
	ds_read_b128 v[176:179], v169 offset:1024
	ds_read_b128 v[180:183], v169 offset:2048
	ds_read_b128 v[184:187], v169 offset:3072
	s_add_u32 s8, s6, 0xfffc0080
	s_addc_u32 s9, s7, -1
	s_cmp_eq_u32 s41, 12
	s_cselect_b32 s11, s12, s9
	s_cselect_b32 s10, s13, s8
	s_cselect_b32 s9, s14, s17
	s_cselect_b32 s8, s15, s16
	v_lshl_add_u64 v[220:221], s[6:7], 0, v[138:139]
	s_add_i32 m0, s50, 0xc000
	ds_read_b128 v[188:191], v170
	ds_read_b128 v[192:195], v170 offset:1024
	ds_read_b128 v[196:199], v170 offset:2048
	ds_read_b128 v[200:203], v170 offset:3072
	ds_read_b128 v[204:207], v170 offset:4096
	ds_read_b128 v[208:211], v170 offset:5120
	ds_read_b128 v[212:215], v170 offset:6144
	ds_read_b128 v[216:219], v170 offset:7168
	global_load_lds_dwordx4 v[220:221], off
	v_lshl_add_u64 v[220:221], s[6:7], 0, v[140:141]
	s_add_i32 m0, s50, 0xe000
	s_nop 0
	global_load_lds_dwordx4 v[220:221], off
	s_cmp_lg_u32 s98, 0
	s_cbranch_scc1 .Lmy_rw_p9_0a
	s_waitcnt vmcnt(8)
	s_branch .Lmy_rw_p9_0b

; #define PG8_STAGE(bufoff, gbase, voff) do { _Pragma("unroll") for (int _i = 0; _i < 2; ++_i) \
;         __builtin_amdgcn_global_load_lds((const unsigned*)((const char*)(gbase) + (voff)[_i]), (LAS unsigned*)(lds + (bufoff) + ldsw + _i * 8192), 16, 0, 0); } while (0)
; #define PG8_LDA(dst, b, h) do { _Pragma("unroll") for (int m = 0; m < 4; ++m) _Pragma("unroll") for (int k = 0; k < 2; ++k) dst[m][k] = *(const LAS bf16x8*)(lds + PG8_SA(b, h) + aoff + m * 2048 + k * 1024); } while (0)
; #define PG8_MMA(ai, bj, At, Bt) do { __builtin_amdgcn_s_setprio(3); _Pragma("unroll") for (int m = 0; m < 4; ++m) _Pragma("unroll") for (int n = 0; n < 2; ++n) _Pragma("unroll") for (int k = 0; k < 2; ++k) \
;         acc[ai][bj][m][n] = __builtin_amdgcn_mfma_f32_16x16x32_bf16(Bt[n][k], At[m][k], acc[ai][bj][m][n], 0, 0, 0); __builtin_amdgcn_s_setprio(0); } while (0)
; #define PG8_WAIT_V(n) asm volatile("s_waitcnt vmcnt(" #n ")" ::: "memory")
; #define PG8_WAIT_L(n) asm volatile("s_waitcnt lgkmcnt(" #n ")" ::: "memory")
; #define PG8_BAR __builtin_amdgcn_s_barrier()
; #define PG8_SCHED __builtin_amdgcn_sched_barrier(0)
; template <class Epi, bool ALIGN_EPI>
; __device__ __forceinline__ void gemm_phase(LAS unsigned char* lds, const Gemm g, const StaticOrder& S, const Epi& E) {
;     ...
;             PG8_WAIT_V(8); PG8_WAIT_L(0); PG8_BAR; PG8_MMA(0, 0, At, B0); PG8_MMA(0, 1, At, B1); PG8_BAR; PG8_SCHED;
;             PG8_LDA(At, 0, 1); PG8_STAGE(PG8_SB(0, 0), b2, voffB); PG8_STAGE(PG8_SB(0, 1), b2 + hstep, voffB); PG8_STAGE(PG8_SA(0, 0), a2, voffA);
.Lmy_rw_p9_0b:
	s_waitcnt lgkmcnt(0)
	s_barrier
	s_setprio 3
	s_waitcnt lgkmcnt(0)
	v_mfma_f32_16x16x32_bf16 v[126:129], v[146:149], v[188:191], 0
	v_mfma_f32_16x16x32_bf16 v[118:121], v[154:157], v[188:191], 0
	v_mfma_f32_16x16x32_bf16 v[110:113], v[146:149], v[196:199], 0
	v_mfma_f32_16x16x32_bf16 v[102:105], v[154:157], v[196:199], 0
	v_mfma_f32_16x16x32_bf16 v[94:97], v[146:149], v[204:207], 0
	v_mfma_f32_16x16x32_bf16 v[86:89], v[154:157], v[204:207], 0
	v_mfma_f32_16x16x32_bf16 v[78:81], v[146:149], v[212:215], 0
	v_mfma_f32_16x16x32_bf16 v[70:73], v[154:157], v[212:215], 0
	v_mfma_f32_16x16x32_bf16 v[126:129], v[150:153], v[192:195], v[126:129]
	v_mfma_f32_16x16x32_bf16 v[118:121], v[158:161], v[192:195], v[118:121]
	v_mfma_f32_16x16x32_bf16 v[110:113], v[150:153], v[200:203], v[110:113]
	v_mfma_f32_16x16x32_bf16 v[102:105], v[158:161], v[200:203], v[102:105]
	v_mfma_f32_16x16x32_bf16 v[94:97], v[150:153], v[208:211], v[94:97]
	v_mfma_f32_16x16x32_bf16 v[86:89], v[158:161], v[208:211], v[86:89]
	v_mfma_f32_16x16x32_bf16 v[78:81], v[150:153], v[216:219], v[78:81]
	v_mfma_f32_16x16x32_bf16 v[70:73], v[158:161], v[216:219], v[70:73]
	v_mfma_f32_16x16x32_bf16 v[122:125], v[172:175], v[188:191], 0
	v_mfma_f32_16x16x32_bf16 v[114:117], v[180:183], v[188:191], 0
	v_mfma_f32_16x16x32_bf16 v[106:109], v[172:175], v[196:199], 0
	v_mfma_f32_16x16x32_bf16 v[98:101], v[180:183], v[196:199], 0
	v_mfma_f32_16x16x32_bf16 v[90:93], v[172:175], v[204:207], 0
	v_mfma_f32_16x16x32_bf16 v[82:85], v[180:183], v[204:207], 0
	v_mfma_f32_16x16x32_bf16 v[74:77], v[172:175], v[212:215], 0
	v_mfma_f32_16x16x32_bf16 v[66:69], v[180:183], v[212:215], 0
	v_mfma_f32_16x16x32_bf16 v[122:125], v[176:179], v[192:195], v[122:125]
	v_mfma_f32_16x16x32_bf16 v[114:117], v[184:187], v[192:195], v[114:117]
	v_mfma_f32_16x16x32_bf16 v[106:109], v[176:179], v[200:203], v[106:109]
	v_mfma_f32_16x16x32_bf16 v[98:101], v[184:187], v[200:203], v[98:101]
	v_mfma_f32_16x16x32_bf16 v[90:93], v[176:179], v[208:211], v[90:93]
	v_mfma_f32_16x16x32_bf16 v[82:85], v[184:187], v[208:211], v[82:85]
	v_mfma_f32_16x16x32_bf16 v[74:77], v[176:179], v[216:219], v[74:77]
	v_mfma_f32_16x16x32_bf16 v[66:69], v[184:187], v[216:219], v[66:69]
	s_setprio 0
	s_barrier
	s_add_i32 s43, s58, s33
	v_lshl_add_u64 v[220:221], s[8:9], 0, v[132:133]
	s_mov_b32 m0, s43
	ds_read_b128 v[188:191], v170 offset:16384
	ds_read_b128 v[192:195], v170 offset:17408
	ds_read_b128 v[196:199], v170 offset:18432
	ds_read_b128 v[200:203], v170 offset:19456
	ds_read_b128 v[204:207], v170 offset:20480
	ds_read_b128 v[208:211], v170 offset:21504
	ds_read_b128 v[212:215], v170 offset:22528
	ds_read_b128 v[216:219], v170 offset:23552
	global_load_lds_dwordx4 v[220:221], off
	s_add_i32 m0, s43, 0x2000
	s_add_u32 s62, s8, 0x40000
	v_lshl_add_u64 v[222:223], s[8:9], 0, v[136:137]
	s_addc_u32 s63, s9, 0
	s_add_i32 s43, s59, s33
	global_load_lds_dwordx4 v[222:223], off
	v_lshl_add_u64 v[224:225], s[62:63], 0, v[132:133]
	s_mov_b32 m0, s43
	v_lshl_add_u64 v[226:227], s[10:11], 0, v[134:135]
	global_load_lds_dwordx4 v[224:225], off
	v_lshl_add_u64 v[224:225], s[62:63], 0, v[136:137]
	s_add_i32 m0, s43, 0x2000
	s_nop 0
	global_load_lds_dwordx4 v[224:225], off
	v_lshl_add_u64 v[224:225], s[10:11], 0, v[130:131]
	s_mov_b32 m0, s50
	s_nop 0
	global_load_lds_dwordx4 v[224:225], off
	s_mov_b32 m0, s51
	s_nop 0
	global_load_lds_dwordx4 v[226:227], off
	s_cmp_lg_u32 s98, 0
	s_cbranch_scc1 .Lmy_rw_p9_1a
	s_waitcnt vmcnt(8)
	s_branch .Lmy_rw_p9_1b

; #define PG8_STAGE(bufoff, gbase, voff) do { _Pragma("unroll") for (int _i = 0; _i < 2; ++_i) \
;         __builtin_amdgcn_global_load_lds((const unsigned*)((const char*)(gbase) + (voff)[_i]), (LAS unsigned*)(lds + (bufoff) + ldsw + _i * 8192), 16, 0, 0); } while (0)
; #define PG8_LDA(dst, b, h) do { _Pragma("unroll") for (int m = 0; m < 4; ++m) _Pragma("unroll") for (int k = 0; k < 2; ++k) dst[m][k] = *(const LAS bf16x8*)(lds + PG8_SA(b, h) + aoff + m * 2048 + k * 1024); } while (0)
; #define PG8_LDB(dst, b, h) do { _Pragma("unroll") for (int n = 0; n < 2; ++n) _Pragma("unroll") for (int k = 0; k < 2; ++k) dst[n][k] = *(const LAS bf16x8*)(lds + PG8_SB(b, h) + boff + n * 2048 + k * 1024); } while (0)
; #define PG8_MMA(ai, bj, At, Bt) do { __builtin_amdgcn_s_setprio(3); _Pragma("unroll") for (int m = 0; m < 4; ++m) _Pragma("unroll") for (int n = 0; n < 2; ++n) _Pragma("unroll") for (int k = 0; k < 2; ++k) \
;         acc[ai][bj][m][n] = __builtin_amdgcn_mfma_f32_16x16x32_bf16(Bt[n][k], At[m][k], acc[ai][bj][m][n], 0, 0, 0); __builtin_amdgcn_s_setprio(0); } while (0)
; #define PG8_WAIT_V(n) asm volatile("s_waitcnt vmcnt(" #n ")" ::: "memory")
; #define PG8_WAIT_L(n) asm volatile("s_waitcnt lgkmcnt(" #n ")" ::: "memory")
; #define PG8_BAR __builtin_amdgcn_s_barrier()
; #define PG8_SCHED __builtin_amdgcn_sched_barrier(0)
; template <class Epi, bool ALIGN_EPI>
; __device__ __forceinline__ void gemm_phase(LAS unsigned char* lds, const Gemm g, const StaticOrder& S, const Epi& E) {
;     ...
;             PG8_LDA(At, 0, 1); PG8_STAGE(PG8_SB(0, 0), b2, voffB); PG8_STAGE(PG8_SB(0, 1), b2 + hstep, voffB); PG8_STAGE(PG8_SA(0, 0), a2, voffA);
;             PG8_WAIT_V(8); PG8_WAIT_L(0); PG8_BAR; PG8_MMA(1, 0, At, B0); PG8_MMA(1, 1, At, B1); PG8_BAR; PG8_SCHED;
;             PG8_LDB(B0, 1, 0); PG8_LDB(B1, 1, 1); PG8_SCHED; PG8_LDA(At, 1, 0); PG8_STAGE(PG8_SA(0, 1), a2 + hstep, voffA);
;             PG8_WAIT_V(8); PG8_WAIT_L(0); PG8_BAR; PG8_MMA(0, 0, At, B0); PG8_MMA(0, 1, At, B1); PG8_BAR; PG8_SCHED;
.Lmy_rw_p9_1b:
	s_waitcnt lgkmcnt(0)
	s_barrier
	s_setprio 3
	s_waitcnt lgkmcnt(0)
	v_mfma_f32_16x16x32_bf16 v[62:65], v[146:149], v[188:191], 0
	v_mfma_f32_16x16x32_bf16 v[54:57], v[154:157], v[188:191], 0
	v_mfma_f32_16x16x32_bf16 v[46:49], v[146:149], v[196:199], 0
	v_mfma_f32_16x16x32_bf16 v[38:41], v[154:157], v[196:199], 0
	v_mfma_f32_16x16x32_bf16 v[30:33], v[146:149], v[204:207], 0
	v_mfma_f32_16x16x32_bf16 v[22:25], v[154:157], v[204:207], 0
	v_mfma_f32_16x16x32_bf16 v[14:17], v[146:149], v[212:215], 0
	v_mfma_f32_16x16x32_bf16 v[6:9], v[154:157], v[212:215], 0
	v_mfma_f32_16x16x32_bf16 v[62:65], v[150:153], v[192:195], v[62:65]
	v_mfma_f32_16x16x32_bf16 v[54:57], v[158:161], v[192:195], v[54:57]
	v_mfma_f32_16x16x32_bf16 v[46:49], v[150:153], v[200:203], v[46:49]
	v_mfma_f32_16x16x32_bf16 v[38:41], v[158:161], v[200:203], v[38:41]
	v_mfma_f32_16x16x32_bf16 v[30:33], v[150:153], v[208:211], v[30:33]
	v_mfma_f32_16x16x32_bf16 v[22:25], v[158:161], v[208:211], v[22:25]
	v_mfma_f32_16x16x32_bf16 v[14:17], v[150:153], v[216:219], v[14:17]
	v_mfma_f32_16x16x32_bf16 v[6:9], v[158:161], v[216:219], v[6:9]
	v_mfma_f32_16x16x32_bf16 v[58:61], v[172:175], v[188:191], 0
	v_mfma_f32_16x16x32_bf16 v[50:53], v[180:183], v[188:191], 0
	v_mfma_f32_16x16x32_bf16 v[42:45], v[172:175], v[196:199], 0
	v_mfma_f32_16x16x32_bf16 v[34:37], v[180:183], v[196:199], 0
	v_mfma_f32_16x16x32_bf16 v[26:29], v[172:175], v[204:207], 0
	v_mfma_f32_16x16x32_bf16 v[18:21], v[180:183], v[204:207], 0
	v_mfma_f32_16x16x32_bf16 v[10:13], v[172:175], v[212:215], 0
	v_mfma_f32_16x16x32_bf16 v[2:5], v[180:183], v[212:215], 0
	v_mfma_f32_16x16x32_bf16 v[58:61], v[176:179], v[192:195], v[58:61]
	v_mfma_f32_16x16x32_bf16 v[50:53], v[184:187], v[192:195], v[50:53]
	v_mfma_f32_16x16x32_bf16 v[42:45], v[176:179], v[200:203], v[42:45]
	v_mfma_f32_16x16x32_bf16 v[34:37], v[184:187], v[200:203], v[34:37]
	v_mfma_f32_16x16x32_bf16 v[26:29], v[176:179], v[208:211], v[26:29]
	v_mfma_f32_16x16x32_bf16 v[18:21], v[184:187], v[208:211], v[18:21]
	v_mfma_f32_16x16x32_bf16 v[10:13], v[176:179], v[216:219], v[10:13]
	v_mfma_f32_16x16x32_bf16 v[2:5], v[184:187], v[216:219], v[2:5]
	s_setprio 0
	s_barrier
	s_add_i32 s43, 0, 0x18000
	s_add_i32 s62, 0, 0x1c000
	v_add_u32_e32 v158, s43, v166
	v_add_u32_e32 v184, s62, v166
	ds_read_b128 v[146:149], v158
	ds_read_b128 v[150:153], v158 offset:1024
	ds_read_b128 v[154:157], v158 offset:2048
	ds_read_b128 v[158:161], v158 offset:3072
	ds_read_b128 v[172:175], v184
	ds_read_b128 v[176:179], v184 offset:1024
	ds_read_b128 v[180:183], v184 offset:2048
	ds_read_b128 v[184:187], v184 offset:3072
	s_add_u32 s10, s10, 0x40000
	s_addc_u32 s11, s11, 0
	s_mov_b32 m0, s52
	v_lshl_add_u64 v[228:229], s[10:11], 0, v[130:131]
	ds_read_b128 v[188:191], v170 offset:32768
	ds_read_b128 v[192:195], v170 offset:33792
	ds_read_b128 v[196:199], v170 offset:34816
	ds_read_b128 v[200:203], v170 offset:35840
	ds_read_b128 v[204:207], v170 offset:36864
	ds_read_b128 v[208:211], v170 offset:37888
	ds_read_b128 v[212:215], v170 offset:38912
	ds_read_b128 v[216:219], v170 offset:39936
	global_load_lds_dwordx4 v[228:229], off
	v_lshl_add_u64 v[228:229], s[10:11], 0, v[134:135]
	s_mov_b32 m0, s53
	s_nop 0
	global_load_lds_dwordx4 v[228:229], off
	s_waitcnt vmcnt(8)
	s_waitcnt lgkmcnt(0)
	s_barrier
	s_setprio 3
	s_waitcnt lgkmcnt(0)
	v_mfma_f32_16x16x32_bf16 v[126:129], v[146:149], v[188:191], v[126:129]
	v_mfma_f32_16x16x32_bf16 v[118:121], v[154:157], v[188:191], v[118:121]
	v_mfma_f32_16x16x32_bf16 v[110:113], v[146:149], v[196:199], v[110:113]
	v_mfma_f32_16x16x32_bf16 v[102:105], v[154:157], v[196:199], v[102:105]
	v_mfma_f32_16x16x32_bf16 v[94:97], v[146:149], v[204:207], v[94:97]
	v_mfma_f32_16x16x32_bf16 v[86:89], v[154:157], v[204:207], v[86:89]
	v_mfma_f32_16x16x32_bf16 v[78:81], v[146:149], v[212:215], v[78:81]
	v_mfma_f32_16x16x32_bf16 v[70:73], v[154:157], v[212:215], v[70:73]
	v_mfma_f32_16x16x32_bf16 v[126:129], v[150:153], v[192:195], v[126:129]
	v_mfma_f32_16x16x32_bf16 v[118:121], v[158:161], v[192:195], v[118:121]
	v_mfma_f32_16x16x32_bf16 v[110:113], v[150:153], v[200:203], v[110:113]
	v_mfma_f32_16x16x32_bf16 v[102:105], v[158:161], v[200:203], v[102:105]
	v_mfma_f32_16x16x32_bf16 v[94:97], v[150:153], v[208:211], v[94:97]
	v_mfma_f32_16x16x32_bf16 v[86:89], v[158:161], v[208:211], v[86:89]
	v_mfma_f32_16x16x32_bf16 v[78:81], v[150:153], v[216:219], v[78:81]
	v_mfma_f32_16x16x32_bf16 v[70:73], v[158:161], v[216:219], v[70:73]
	v_mfma_f32_16x16x32_bf16 v[122:125], v[172:175], v[188:191], v[122:125]
	v_mfma_f32_16x16x32_bf16 v[114:117], v[180:183], v[188:191], v[114:117]
	v_mfma_f32_16x16x32_bf16 v[106:109], v[172:175], v[196:199], v[106:109]
	v_mfma_f32_16x16x32_bf16 v[98:101], v[180:183], v[196:199], v[98:101]
	v_mfma_f32_16x16x32_bf16 v[90:93], v[172:175], v[204:207], v[90:93]
	v_mfma_f32_16x16x32_bf16 v[82:85], v[180:183], v[204:207], v[82:85]
	v_mfma_f32_16x16x32_bf16 v[74:77], v[172:175], v[212:215], v[74:77]
	v_mfma_f32_16x16x32_bf16 v[66:69], v[180:183], v[212:215], v[66:69]
	v_mfma_f32_16x16x32_bf16 v[122:125], v[176:179], v[192:195], v[122:125]
	v_mfma_f32_16x16x32_bf16 v[114:117], v[184:187], v[192:195], v[114:117]
	v_mfma_f32_16x16x32_bf16 v[106:109], v[176:179], v[200:203], v[106:109]
	v_mfma_f32_16x16x32_bf16 v[98:101], v[184:187], v[200:203], v[98:101]
	v_mfma_f32_16x16x32_bf16 v[90:93], v[176:179], v[208:211], v[90:93]
	v_mfma_f32_16x16x32_bf16 v[82:85], v[184:187], v[208:211], v[82:85]
	v_mfma_f32_16x16x32_bf16 v[74:77], v[176:179], v[216:219], v[74:77]
	v_mfma_f32_16x16x32_bf16 v[66:69], v[184:187], v[216:219], v[66:69]
	s_setprio 0
	s_barrier
; #define PG8_STAGE(bufoff, gbase, voff) do { _Pragma("unroll") for (int _i = 0; _i < 2; ++_i) \
;         __builtin_amdgcn_global_load_lds((const unsigned*)((const char*)(gbase) + (voff)[_i]), (LAS unsigned*)(lds + (bufoff) + ldsw + _i * 8192), 16, 0, 0); } while (0)
; #define PG8_LDA(dst, b, h) do { _Pragma("unroll") for (int m = 0; m < 4; ++m) _Pragma("unroll") for (int k = 0; k < 2; ++k) dst[m][k] = *(const LAS bf16x8*)(lds + PG8_SA(b, h) + aoff + m * 2048 + k * 1024); } while (0)
; #define PG8_MMA(ai, bj, At, Bt) do { __builtin_amdgcn_s_setprio(3); _Pragma("unroll") for (int m = 0; m < 4; ++m) _Pragma("unroll") for (int n = 0; n < 2; ++n) _Pragma("unroll") for (int k = 0; k < 2; ++k) \
;         acc[ai][bj][m][n] = __builtin_amdgcn_mfma_f32_16x16x32_bf16(Bt[n][k], At[m][k], acc[ai][bj][m][n], 0, 0, 0); __builtin_amdgcn_s_setprio(0); } while (0)
; #define PG8_WAIT_V(n) asm volatile("s_waitcnt vmcnt(" #n ")" ::: "memory")
; #define PG8_WAIT_L(n) asm volatile("s_waitcnt lgkmcnt(" #n ")" ::: "memory")
; #define PG8_BAR __builtin_amdgcn_s_barrier()
; #define PG8_SCHED __builtin_amdgcn_sched_barrier(0)
; template <class Epi, bool ALIGN_EPI>
; __device__ __forceinline__ void gemm_phase(LAS unsigned char* lds, const Gemm g, const StaticOrder& S, const Epi& E) {
;     ...
;             PG8_LDA(At, 1, 1); PG8_STAGE(PG8_SB(1, 0), b3, voffB); PG8_STAGE(PG8_SB(1, 1), b3 + hstep, voffB); PG8_STAGE(PG8_SA(1, 0), a3, voffA);
;             PG8_WAIT_V(8); PG8_WAIT_L(0); PG8_BAR; PG8_MMA(1, 0, At, B0); PG8_MMA(1, 1, At, B1); PG8_BAR; PG8_SCHED;
	s_add_i32 s10, s43, s33
	v_lshl_add_u64 v[220:221], v[220:221], 0, s[36:37]
	s_mov_b32 m0, s10
	ds_read_b128 v[188:191], v170 offset:49152
	ds_read_b128 v[192:195], v170 offset:50176
	ds_read_b128 v[196:199], v170 offset:51200
	ds_read_b128 v[200:203], v170 offset:52224
	ds_read_b128 v[204:207], v170 offset:53248
	ds_read_b128 v[208:211], v170 offset:54272
	ds_read_b128 v[212:215], v170 offset:55296
	ds_read_b128 v[216:219], v170 offset:56320
	global_load_lds_dwordx4 v[220:221], off
	s_add_i32 m0, s10, 0x2000
	s_add_u32 s8, s8, 0x40080
	v_lshl_add_u64 v[220:221], v[222:223], 0, s[36:37]
	s_addc_u32 s9, s9, 0
	s_add_i32 s10, s62, s33
	global_load_lds_dwordx4 v[220:221], off
	v_lshl_add_u64 v[220:221], s[8:9], 0, v[132:133]
	s_mov_b32 m0, s10
	s_nop 0
	global_load_lds_dwordx4 v[220:221], off
	v_lshl_add_u64 v[220:221], s[8:9], 0, v[136:137]
	s_add_i32 m0, s10, 0x2000
	s_nop 0
	global_load_lds_dwordx4 v[220:221], off
	v_lshl_add_u64 v[220:221], v[224:225], 0, s[36:37]
	s_mov_b32 m0, s56
	s_nop 0
	global_load_lds_dwordx4 v[220:221], off
	v_lshl_add_u64 v[220:221], v[226:227], 0, s[36:37]
	s_mov_b32 m0, s57
	s_nop 0
	global_load_lds_dwordx4 v[220:221], off
	s_waitcnt vmcnt(8)
	s_waitcnt lgkmcnt(0)
	s_barrier
	s_setprio 3
	s_waitcnt lgkmcnt(0)
	v_mfma_f32_16x16x32_bf16 v[62:65], v[146:149], v[188:191], v[62:65]
	v_mfma_f32_16x16x32_bf16 v[54:57], v[154:157], v[188:191], v[54:57]
	v_mfma_f32_16x16x32_bf16 v[46:49], v[146:149], v[196:199], v[46:49]
	v_mfma_f32_16x16x32_bf16 v[38:41], v[154:157], v[196:199], v[38:41]
	v_mfma_f32_16x16x32_bf16 v[30:33], v[146:149], v[204:207], v[30:33]
	v_mfma_f32_16x16x32_bf16 v[22:25], v[154:157], v[204:207], v[22:25]
	v_mfma_f32_16x16x32_bf16 v[14:17], v[146:149], v[212:215], v[14:17]
	v_mfma_f32_16x16x32_bf16 v[6:9], v[154:157], v[212:215], v[6:9]
	v_mfma_f32_16x16x32_bf16 v[62:65], v[150:153], v[192:195], v[62:65]
	v_mfma_f32_16x16x32_bf16 v[54:57], v[158:161], v[192:195], v[54:57]
	v_mfma_f32_16x16x32_bf16 v[46:49], v[150:153], v[200:203], v[46:49]
	v_mfma_f32_16x16x32_bf16 v[38:41], v[158:161], v[200:203], v[38:41]
	v_mfma_f32_16x16x32_bf16 v[30:33], v[150:153], v[208:211], v[30:33]
	v_mfma_f32_16x16x32_bf16 v[22:25], v[158:161], v[208:211], v[22:25]
	v_mfma_f32_16x16x32_bf16 v[14:17], v[150:153], v[216:219], v[14:17]
	v_mfma_f32_16x16x32_bf16 v[6:9], v[158:161], v[216:219], v[6:9]
	v_mfma_f32_16x16x32_bf16 v[58:61], v[172:175], v[188:191], v[58:61]
	v_mfma_f32_16x16x32_bf16 v[50:53], v[180:183], v[188:191], v[50:53]
	v_mfma_f32_16x16x32_bf16 v[42:45], v[172:175], v[196:199], v[42:45]
	v_mfma_f32_16x16x32_bf16 v[34:37], v[180:183], v[196:199], v[34:37]
	v_mfma_f32_16x16x32_bf16 v[26:29], v[172:175], v[204:207], v[26:29]
	v_mfma_f32_16x16x32_bf16 v[18:21], v[180:183], v[204:207], v[18:21]
	v_mfma_f32_16x16x32_bf16 v[10:13], v[172:175], v[212:215], v[10:13]
	v_mfma_f32_16x16x32_bf16 v[2:5], v[180:183], v[212:215], v[2:5]
	v_mfma_f32_16x16x32_bf16 v[58:61], v[176:179], v[192:195], v[58:61]
	v_mfma_f32_16x16x32_bf16 v[50:53], v[184:187], v[192:195], v[50:53]
	v_mfma_f32_16x16x32_bf16 v[42:45], v[176:179], v[200:203], v[42:45]
	v_mfma_f32_16x16x32_bf16 v[34:37], v[184:187], v[200:203], v[34:37]
	v_mfma_f32_16x16x32_bf16 v[26:29], v[176:179], v[208:211], v[26:29]
	v_mfma_f32_16x16x32_bf16 v[18:21], v[184:187], v[208:211], v[18:21]
	v_mfma_f32_16x16x32_bf16 v[10:13], v[176:179], v[216:219], v[10:13]
	v_mfma_f32_16x16x32_bf16 v[2:5], v[184:187], v[216:219], v[2:5]
	s_setprio 0
	s_barrier
	s_add_i32 s41, s41, 2
	s_add_u32 s6, s6, 0x100
	s_addc_u32 s7, s7, 0
	s_add_u32 s16, s16, 0x100
	s_addc_u32 s17, s17, 0
